# attention inner loop rewritten by hand: per-lane max3 + rare-path rescale, hoisted constants, K/V fragment prefetch
# speedup vs baseline: 1.0390x; 1.0390x over previous
; __device__ __forceinline__ void attn_unit(LAS unsigned char* lds, const bf16_t* Q, const bf16_t* KV, const bf16_t* KR, bf16_t* MIX, size_t qrow0, size_t krow0, int ntiles, int h, const int tid) {
;     ...
;   const bf16x8 ones = (bf16x8){0x3F80, 0x3F80, 0x3F80, 0x3F80, 0x3F80, 0x3F80, 0x3F80, 0x3F80};
;   u32x4 rk = *(const u32x4*)gk, rv = *(const u32x4*)(gk + 64), rr = (u32x4){0, 0, 0, 0};
;   if (tid < 256) rr = *(const u32x4*)gr;
;   __syncthreads();
;   attn_stage(lds, tid, rk, rv, rr);
;   __syncthreads();
;     ...
;     for (int qb = 0; qb < 2; ++qb) {
;       float mx = -1e30f;
; #pragma unroll
;       for (int kb = 0; kb < 4; ++kb) mx = fmaxf(fmaxf(fmaxf(s[kb][qb][0], s[kb][qb][1]), fmaxf(s[kb][qb][2], s[kb][qb][3])), mx);
;       mx = fmaxf(mx, __shfl_xor(mx, 16)); mx = fmaxf(mx, __shfl_xor(mx, 32));
;       if (t == 0 || __any(mx > 8.f)) {
;         const float delta = (t == 0) ? mx : fmaxf(mx, 0.f), alpha = (t == 0) ? 1.f : __builtin_amdgcn_exp2f(-delta);
;         mref[qb] += delta; lacc[qb] = lacc[qb] * alpha;
; #pragma unroll
;         for (int kb = 0; kb < 4; ++kb) s[kb][qb] = s[kb][qb] - delta;
; #pragma unroll
;         for (int eb = 0; eb < 4; ++eb) o[qb][eb] = o[qb][eb] * alpha;
;       }
.LBB0_382:
	s_or_b64 exec, exec, s[4:5]
	s_and_b32 s4, s8, 7
	s_mul_i32 s5, s4, 0x84000
	s_mul_i32 s4, s4, 0x1080000
	s_lshl_b64 s[0:1], s[0:1], 1
	s_add_u32 s0, s4, s0
	v_or_b32_e32 v0, s5, v121
	s_addc_u32 s1, 0, s1
	v_pk_add_f32 v[2:3], v[2:3], 0 op_sel_hi:[1,0]
	v_lshl_add_u64 v[140:141], v[132:133], 0, v[0:1]
	v_lshl_add_u64 v[142:143], v[134:135], 0, s[0:1]
	s_mov_b32 s4, 2
	s_waitcnt vmcnt(0)
	ds_write_b128 v151, v[72:75] offset:35840
	s_waitcnt lgkmcnt(0)
	s_barrier
	v_mov_b32_e32 v198, 0x3f803f80
	v_mov_b32_e32 v199, v198
	v_mov_b32_e32 v200, v198
	v_mov_b32_e32 v201, v198
	v_xor_b32_e32 v202, 0x80000000, v2
	v_xor_b32_e32 v206, 0x80000000, v3
	v_lshlrev_b32_e32 v176, 1, v154
	v_mov_b32_e32 v203, v202
	v_mov_b32_e32 v204, v202
	v_mov_b32_e32 v205, v202
	v_mov_b32_e32 v207, v206
	v_mov_b32_e32 v208, v206
	v_mov_b32_e32 v209, v206
	s_branch .LBB0_384
.Lat_rare:
	s_waitcnt lgkmcnt(0)
	ds_bpermute_b32 v177, v152, v174
	s_waitcnt lgkmcnt(0)
	v_max_f32_e32 v174, v174, v177
	ds_bpermute_b32 v177, v153, v174
	s_waitcnt lgkmcnt(0)
	v_max_f32_e32 v174, v174, v177
	v_cmp_lt_f32_e32 vcc, 0x41000000, v174
	s_cbranch_vccz .Lat_rare1
	v_max_f32_e32 v182, 0, v174
	v_exp_f32_e64 v0, -v182
	v_add_f32_e32 v2, v2, v182
	v_sub_f32_e32 v80, v80, v182
	v_sub_f32_e32 v81, v81, v182
	v_sub_f32_e32 v82, v82, v182
	v_sub_f32_e32 v83, v83, v182
	v_sub_f32_e32 v84, v84, v182
	v_sub_f32_e32 v85, v85, v182
	v_sub_f32_e32 v86, v86, v182
	v_sub_f32_e32 v87, v87, v182
	v_sub_f32_e32 v96, v96, v182
	v_sub_f32_e32 v97, v97, v182
	v_sub_f32_e32 v98, v98, v182
	v_sub_f32_e32 v99, v99, v182
	v_sub_f32_e32 v100, v100, v182
	v_sub_f32_e32 v101, v101, v182
	v_sub_f32_e32 v102, v102, v182
	v_sub_f32_e32 v103, v103, v182
	v_pk_mul_f32 v[62:63], v[62:63], v[0:1] op_sel_hi:[1,0]
	v_pk_mul_f32 v[60:61], v[60:61], v[0:1] op_sel_hi:[1,0]
	v_pk_mul_f32 v[54:55], v[54:55], v[0:1] op_sel_hi:[1,0]
	v_pk_mul_f32 v[52:53], v[52:53], v[0:1] op_sel_hi:[1,0]
	v_pk_mul_f32 v[70:71], v[70:71], v[0:1] op_sel_hi:[1,0]
	v_pk_mul_f32 v[68:69], v[68:69], v[0:1] op_sel_hi:[1,0]
	v_pk_mul_f32 v[46:47], v[46:47], v[0:1] op_sel_hi:[1,0]
	v_pk_mul_f32 v[44:45], v[44:45], v[0:1] op_sel_hi:[1,0]
	v_pk_mul_f32 v[38:39], v[38:39], v[0:1] op_sel_hi:[1,0]
	v_pk_mul_f32 v[36:37], v[36:37], v[0:1] op_sel_hi:[1,0]
	v_xor_b32_e32 v202, 0x80000000, v2
	v_mov_b32_e32 v203, v202
	v_mov_b32_e32 v204, v202
	v_mov_b32_e32 v205, v202
.Lat_rare1:
	ds_bpermute_b32 v177, v152, v175
	s_waitcnt lgkmcnt(0)
	v_max_f32_e32 v175, v175, v177
	ds_bpermute_b32 v177, v153, v175
	s_waitcnt lgkmcnt(0)
	v_max_f32_e32 v175, v175, v177
	v_cmp_lt_f32_e32 vcc, 0x41000000, v175
	s_cbranch_vccz .Lat_rare2
	v_max_f32_e32 v182, 0, v175
	v_exp_f32_e64 v0, -v182
	v_add_f32_e32 v3, v3, v182
	v_sub_f32_e32 v88, v88, v182
	v_sub_f32_e32 v89, v89, v182
	v_sub_f32_e32 v90, v90, v182
	v_sub_f32_e32 v91, v91, v182
	v_sub_f32_e32 v92, v92, v182
	v_sub_f32_e32 v93, v93, v182
	v_sub_f32_e32 v94, v94, v182
	v_sub_f32_e32 v95, v95, v182
	v_sub_f32_e32 v104, v104, v182
	v_sub_f32_e32 v105, v105, v182
	v_sub_f32_e32 v106, v106, v182
	v_sub_f32_e32 v107, v107, v182
	v_sub_f32_e32 v108, v108, v182
	v_sub_f32_e32 v109, v109, v182
	v_sub_f32_e32 v110, v110, v182
	v_sub_f32_e32 v111, v111, v182
	v_pk_mul_f32 v[58:59], v[58:59], v[0:1] op_sel_hi:[1,0]
	v_pk_mul_f32 v[56:57], v[56:57], v[0:1] op_sel_hi:[1,0]
	v_pk_mul_f32 v[50:51], v[50:51], v[0:1] op_sel_hi:[1,0]
	v_pk_mul_f32 v[48:49], v[48:49], v[0:1] op_sel_hi:[1,0]
	v_pk_mul_f32 v[66:67], v[66:67], v[0:1] op_sel_hi:[1,0]
	v_pk_mul_f32 v[64:65], v[64:65], v[0:1] op_sel_hi:[1,0]
	v_pk_mul_f32 v[42:43], v[42:43], v[0:1] op_sel_hi:[1,0]
	v_pk_mul_f32 v[40:41], v[40:41], v[0:1] op_sel_hi:[1,0]
	v_pk_mul_f32 v[34:35], v[34:35], v[0:1] op_sel_hi:[1,0]
	v_pk_mul_f32 v[32:33], v[32:33], v[0:1] op_sel_hi:[1,0]
	v_xor_b32_e32 v206, 0x80000000, v3
	v_mov_b32_e32 v207, v206
	v_mov_b32_e32 v208, v206
	v_mov_b32_e32 v209, v206
.Lat_rare2:
	s_branch .Lat_back

; #define LAS __attribute__((address_space(3)))
; __device__ __forceinline__ f32x4 mfma16(bf16x8 a, bf16x8 b, f32x4 c) { return __builtin_amdgcn_mfma_f32_16x16x32_bf16(a, b, c, 0, 0, 0); }
; __device__ __forceinline__ void attn_unit(LAS unsigned char* lds, const bf16_t* Q, const bf16_t* KV, const bf16_t* KR, bf16_t* MIX, size_t qrow0, size_t krow0, int ntiles, int h, const int tid) {
;     ...
;   for (int t = 0; t < ntiles; ++t) {
;     LAS unsigned char* buf = lds + (t & 1) * AT_BUF;
;     const bool more = (t + 1 < ntiles);
;     if (more) { const bf16_t* g2 = gk + (size_t)(t + 1) * 64 * 1024; rk = *(const u32x4*)g2; rv = *(const u32x4*)(g2 + 64); if (tid < 256) rr = *(const u32x4*)(gr + (size_t)(t + 1) * 64 * 32); }
;     const LAS bf16_t* Ks = (const LAS bf16_t*)buf; const LAS bf16_t* Vs = (const LAS bf16_t*)(buf + 64 * AT_KSTR * 2);
;     f32x4 s[4][2];
; #pragma unroll
;     for (int kb = 0; kb < 4; ++kb) {
;       bf16x8 kf[3];
; #pragma unroll
;       for (int ks = 0; ks < 3; ++ks) kf[ks] = *(const LAS bf16x8*)(Ks + (kb * 16 + c16) * AT_KSTR + ks * 32 + quad * 8);
; #pragma unroll
;       for (int qb = 0; qb < 2; ++qb) { const float nm = -mref[qb]; f32x4 a = (f32x4){nm, nm, nm, nm};
; #pragma unroll
;         for (int ks = 0; ks < 3; ++ks) a = mfma16(kf[ks], qf[qb][ks], a);
;         s[kb][qb] = a; }
;     }
; #pragma unroll
;     for (int qb = 0; qb < 2; ++qb) {
;       float mx = -1e30f;
; #pragma unroll
;       for (int kb = 0; kb < 4; ++kb) mx = fmaxf(fmaxf(fmaxf(s[kb][qb][0], s[kb][qb][1]), fmaxf(s[kb][qb][2], s[kb][qb][3])), mx);
;       mx = fmaxf(mx, __shfl_xor(mx, 16)); mx = fmaxf(mx, __shfl_xor(mx, 32));
;       if (t == 0 || __any(mx > 8.f)) {
.LBB0_386:
	s_or_b64 exec, exec, s[0:1]
	s_and_b32 s0, 1, s4
	s_cselect_b32 s1, 0, 0x5800
	s_cselect_b32 s5, 0x5800, 0
	v_add3_u32 v0, s1, v124, v146
	ds_read_b128 v[158:161], v0
	ds_read_b128 v[162:165], v0 offset:64
	ds_read_b128 v[166:169], v0 offset:128
	ds_read_b128 v[170:173], v0 offset:3328
	ds_read_b128 v[210:213], v0 offset:3392
	ds_read_b128 v[214:217], v0 offset:3456
	ds_read_b128 v[218:221], v0 offset:6656
	ds_read_b128 v[240:243], v0 offset:6720
	ds_read_b128 v[244:247], v0 offset:6784
	v_add3_u32 v139, s1, v176, v155
	s_waitcnt lgkmcnt(8)
	v_mfma_f32_16x16x32_bf16 v[80:83], v[158:161], v[4:7], v[202:205]
	v_mfma_f32_16x16x32_bf16 v[88:91], v[158:161], v[16:19], v[206:209]
	s_waitcnt lgkmcnt(7)
	v_mfma_f32_16x16x32_bf16 v[80:83], v[162:165], v[8:11], v[80:83]
	v_mfma_f32_16x16x32_bf16 v[88:91], v[162:165], v[20:23], v[88:91]
	s_waitcnt lgkmcnt(6)
	v_mfma_f32_16x16x32_bf16 v[80:83], v[166:169], v[12:15], v[80:83]
	v_mfma_f32_16x16x32_bf16 v[88:91], v[166:169], v[24:27], v[88:91]
	ds_read_b128 v[158:161], v0 offset:9984
	ds_read_b128 v[162:165], v0 offset:10048
	ds_read_b128 v[166:169], v0 offset:10112
	s_waitcnt lgkmcnt(8)
	v_mfma_f32_16x16x32_bf16 v[84:87], v[170:173], v[4:7], v[202:205]
	v_mfma_f32_16x16x32_bf16 v[92:95], v[170:173], v[16:19], v[206:209]
	s_waitcnt lgkmcnt(7)
	v_mfma_f32_16x16x32_bf16 v[84:87], v[210:213], v[8:11], v[84:87]
	v_mfma_f32_16x16x32_bf16 v[92:95], v[210:213], v[20:23], v[92:95]
	s_waitcnt lgkmcnt(6)
	v_mfma_f32_16x16x32_bf16 v[84:87], v[214:217], v[12:15], v[84:87]
	v_mfma_f32_16x16x32_bf16 v[92:95], v[214:217], v[24:27], v[92:95]
	ds_read_b64_tr_b16 v[170:171], v139 offset:13312
	ds_read_b64_tr_b16 v[172:173], v139 offset:15616
	ds_read_b64_tr_b16 v[210:211], v139 offset:13344
	ds_read_b64_tr_b16 v[212:213], v139 offset:15648
	ds_read_b64_tr_b16 v[214:215], v139 offset:13376
	ds_read_b64_tr_b16 v[216:217], v139 offset:15680
	s_waitcnt lgkmcnt(11)
	v_mfma_f32_16x16x32_bf16 v[96:99], v[218:221], v[4:7], v[202:205]
	v_mfma_f32_16x16x32_bf16 v[104:107], v[218:221], v[16:19], v[206:209]
	v_max3_f32 v174, v80, v81, v82
	s_waitcnt lgkmcnt(10)
	v_mfma_f32_16x16x32_bf16 v[96:99], v[240:243], v[8:11], v[96:99]
	v_mfma_f32_16x16x32_bf16 v[104:107], v[240:243], v[20:23], v[104:107]
	v_max3_f32 v175, v88, v89, v90
	s_waitcnt lgkmcnt(9)
	v_mfma_f32_16x16x32_bf16 v[96:99], v[244:247], v[12:15], v[96:99]
	v_mfma_f32_16x16x32_bf16 v[104:107], v[244:247], v[24:27], v[104:107]
	ds_read_b64_tr_b16 v[218:219], v139 offset:13408
	ds_read_b64_tr_b16 v[220:221], v139 offset:15712
	s_waitcnt lgkmcnt(10)
	v_mfma_f32_16x16x32_bf16 v[100:103], v[158:161], v[4:7], v[202:205]
	v_mfma_f32_16x16x32_bf16 v[108:111], v[158:161], v[16:19], v[206:209]
	v_max3_f32 v174, v174, v83, v84
	s_waitcnt lgkmcnt(9)
	v_mfma_f32_16x16x32_bf16 v[100:103], v[162:165], v[8:11], v[100:103]
	v_max3_f32 v174, v174, v85, v86
	v_mfma_f32_16x16x32_bf16 v[108:111], v[162:165], v[20:23], v[108:111]
	s_waitcnt lgkmcnt(8)
	v_mfma_f32_16x16x32_bf16 v[100:103], v[166:169], v[12:15], v[100:103]
	v_max3_f32 v175, v175, v91, v92
	v_mfma_f32_16x16x32_bf16 v[108:111], v[166:169], v[24:27], v[108:111]
	v_max3_f32 v175, v175, v93, v94
	v_max3_f32 v174, v174, v87, v96
	v_max3_f32 v174, v174, v97, v98
	v_max3_f32 v175, v175, v95, v104
	v_max3_f32 v175, v175, v105, v106
	ds_read_b64_tr_b16 v[240:241], v139 offset:17920
	ds_read_b64_tr_b16 v[242:243], v139 offset:20224
	ds_read_b64_tr_b16 v[244:245], v139 offset:17952
	ds_read_b64_tr_b16 v[246:247], v139 offset:20256
	ds_read_b64_tr_b16 v[158:159], v139 offset:17984
	ds_read_b64_tr_b16 v[160:161], v139 offset:20288
	v_max3_f32 v174, v174, v99, v100
	v_max3_f32 v175, v175, v107, v108
	v_max3_f32 v174, v174, v101, v102
	v_max3_f32 v175, v175, v109, v110
	v_max_f32_e32 v174, v174, v103
	v_max_f32_e32 v175, v175, v111
	v_max_f32_e32 v0, v174, v175
	v_cmp_lt_f32_e32 vcc, 0x41000000, v0
	s_cbranch_vccnz .Lat_rare
; #define LAS __attribute__((address_space(3)))
; __device__ __forceinline__ unsigned cvtpk(float lo, float hi) { f32x2_t v = {lo, hi}; bf16x2_t b = __builtin_convertvector(v, bf16x2_t); return __builtin_bit_cast(unsigned, b); }
; __device__ __forceinline__ f32x4 mfma16(bf16x8 a, bf16x8 b, f32x4 c) { return __builtin_amdgcn_mfma_f32_16x16x32_bf16(a, b, c, 0, 0, 0); }
; __device__ __forceinline__ u32x2 tr_rd(const LAS bf16_t* p) { return __builtin_bit_cast(u32x2, __builtin_amdgcn_ds_read_tr16_b64_v4i16((LAS v4i16_t*)p)); }
; __device__ __forceinline__ void attn_unit(LAS unsigned char* lds, const bf16_t* Q, const bf16_t* KV, const bf16_t* KR, bf16_t* MIX, size_t qrow0, size_t krow0, int ntiles, int h, const int tid) {
;     ...
; #pragma unroll
;       for (int kb = 0; kb < 4; ++kb)
; #pragma unroll
;         for (int r = 0; r < 4; ++r) s[kb][qb][r] = __builtin_amdgcn_exp2f(s[kb][qb][r]);
;     }
; #pragma unroll
;     for (int s2 = 0; s2 < 2; ++s2) {
;       bf16x8 pf[2];
; #pragma unroll
;       for (int qb = 0; qb < 2; ++qb) { u32x4 w; w.x = cvtpk(s[2 * s2][qb][0], s[2 * s2][qb][1]); w.y = cvtpk(s[2 * s2][qb][2], s[2 * s2][qb][3]);
;         w.z = cvtpk(s[2 * s2 + 1][qb][0], s[2 * s2 + 1][qb][1]); w.w = cvtpk(s[2 * s2 + 1][qb][2], s[2 * s2 + 1][qb][3]); pf[qb] = __builtin_bit_cast(bf16x8, w);
;         lacc[qb] = mfma16(ones, pf[qb], lacc[qb]); }
;       const LAS bf16_t* vb = Vs + (32 * s2 + 4 * quad + tq) * AT_VSTR + 4 * tp;
; #pragma unroll
;       for (int eb = 0; eb < 4; ++eb) {
;         const u32x2 lo = tr_rd(vb + 16 * eb), hi = tr_rd(vb + 16 * AT_VSTR + 16 * eb);
;         const u32x4 vv = (u32x4){lo.x, lo.y, hi.x, hi.y}; const bf16x8 vf = __builtin_bit_cast(bf16x8, vv);
; #pragma unroll
;         for (int qb = 0; qb < 2; ++qb) o[qb][eb] = mfma16(vf, pf[qb], o[qb][eb]);
;       }
;     }
;     if (more) attn_stage(lds + ((t + 1) & 1) * AT_BUF, tid, rk, rv, rr);
;     __syncthreads();
.Lat_back:
	v_exp_f32_e32 v80, v80
	v_exp_f32_e32 v81, v81
	v_exp_f32_e32 v82, v82
	v_exp_f32_e32 v83, v83
	v_exp_f32_e32 v84, v84
	v_exp_f32_e32 v85, v85
	v_exp_f32_e32 v86, v86
	v_exp_f32_e32 v87, v87
	v_cvt_pk_bf16_f32 v80, v80, v81
	v_cvt_pk_bf16_f32 v81, v82, v83
	v_cvt_pk_bf16_f32 v82, v84, v85
	v_cvt_pk_bf16_f32 v83, v86, v87
	v_exp_f32_e32 v88, v88
	v_exp_f32_e32 v89, v89
	v_exp_f32_e32 v90, v90
	v_exp_f32_e32 v91, v91
	v_exp_f32_e32 v92, v92
	v_exp_f32_e32 v93, v93
	v_exp_f32_e32 v94, v94
	v_exp_f32_e32 v95, v95
	v_cvt_pk_bf16_f32 v88, v88, v89
	v_cvt_pk_bf16_f32 v89, v90, v91
	v_cvt_pk_bf16_f32 v90, v92, v93
	v_cvt_pk_bf16_f32 v91, v94, v95
	s_waitcnt lgkmcnt(12)
	v_mfma_f32_16x16x32_bf16 v[52:55], v[170:173], v[80:83], v[52:55]
	v_exp_f32_e32 v96, v96
	v_exp_f32_e32 v97, v97
	v_mfma_f32_16x16x32_bf16 v[48:51], v[170:173], v[88:91], v[48:51]
	v_exp_f32_e32 v98, v98
	v_exp_f32_e32 v99, v99
	v_mfma_f32_16x16x32_bf16 v[60:63], v[198:201], v[80:83], v[60:63]
	v_exp_f32_e32 v100, v100
	v_exp_f32_e32 v101, v101
	v_mfma_f32_16x16x32_bf16 v[56:59], v[198:201], v[88:91], v[56:59]
	v_exp_f32_e32 v102, v102
	v_exp_f32_e32 v103, v103
	s_waitcnt lgkmcnt(10)
	v_mfma_f32_16x16x32_bf16 v[68:71], v[210:213], v[80:83], v[68:71]
	v_exp_f32_e32 v104, v104
	v_exp_f32_e32 v105, v105
	v_mfma_f32_16x16x32_bf16 v[64:67], v[210:213], v[88:91], v[64:67]
	v_exp_f32_e32 v106, v106
	v_exp_f32_e32 v107, v107
	s_waitcnt lgkmcnt(8)
	v_mfma_f32_16x16x32_bf16 v[44:47], v[214:217], v[80:83], v[44:47]
	v_exp_f32_e32 v108, v108
	v_exp_f32_e32 v109, v109
	v_mfma_f32_16x16x32_bf16 v[40:43], v[214:217], v[88:91], v[40:43]
	v_exp_f32_e32 v110, v110
	v_exp_f32_e32 v111, v111
	s_waitcnt lgkmcnt(6)
	v_mfma_f32_16x16x32_bf16 v[36:39], v[218:221], v[80:83], v[36:39]
	v_cvt_pk_bf16_f32 v96, v96, v97
	v_cvt_pk_bf16_f32 v97, v98, v99
	v_mfma_f32_16x16x32_bf16 v[32:35], v[218:221], v[88:91], v[32:35]
	v_cvt_pk_bf16_f32 v98, v100, v101
	v_cvt_pk_bf16_f32 v99, v102, v103
	ds_read_b64_tr_b16 v[162:163], v139 offset:18016
	ds_read_b64_tr_b16 v[164:165], v139 offset:20320
	v_cvt_pk_bf16_f32 v104, v104, v105
	v_cvt_pk_bf16_f32 v105, v106, v107
	v_cvt_pk_bf16_f32 v106, v108, v109
	v_cvt_pk_bf16_f32 v107, v110, v111
	v_mfma_f32_16x16x32_bf16 v[60:63], v[198:201], v[96:99], v[60:63]
	v_add3_u32 v0, s5, v148, v138
	v_add3_u32 v177, s5, v127, v138
	v_mfma_f32_16x16x32_bf16 v[56:59], v[198:201], v[104:107], v[56:59]
	s_waitcnt lgkmcnt(6)
	v_mfma_f32_16x16x32_bf16 v[52:55], v[240:243], v[96:99], v[52:55]
	v_mfma_f32_16x16x32_bf16 v[48:51], v[240:243], v[104:107], v[48:51]
	s_waitcnt lgkmcnt(4)
	v_mfma_f32_16x16x32_bf16 v[68:71], v[244:247], v[96:99], v[68:71]
	v_mfma_f32_16x16x32_bf16 v[64:67], v[244:247], v[104:107], v[64:67]
	s_waitcnt lgkmcnt(2)
	v_mfma_f32_16x16x32_bf16 v[44:47], v[158:161], v[96:99], v[44:47]
	v_mfma_f32_16x16x32_bf16 v[40:43], v[158:161], v[104:107], v[40:43]
	s_waitcnt lgkmcnt(0)
	v_mfma_f32_16x16x32_bf16 v[36:39], v[162:165], v[96:99], v[36:39]
	v_mfma_f32_16x16x32_bf16 v[32:35], v[162:165], v[104:107], v[32:35]
	s_waitcnt vmcnt(0)
	ds_write_b128 v0, v[76:79]
	ds_write_b128 v177, v[72:75] offset:13312
	s_and_saveexec_b64 s[0:1], s[42:43]
	s_cbranch_execz .LBB0_383
	v_add3_u32 v0, s5, v149, v126
	ds_write_b128 v0, v[28:31] offset:128
.LBB0_383:
	s_or_b64 exec, exec, s[0:1]
	s_mov_b64 s[0:1], 0x1000
	s_add_i32 s4, s4, 1
	v_lshl_add_u64 v[140:141], v[140:141], 0, s[0:1]
	s_mov_b64 s[0:1], 0x20000
	v_lshl_add_u64 v[142:143], v[142:143], 0, s[0:1]
	s_cmpk_lg_i32 s4, 0x84
	s_waitcnt lgkmcnt(0)
	s_barrier
	s_cbranch_scc1 .LBB0_384
